# FFN2-up GEMM epilogue: the 8 per-row-block RMSNorm partial-sum loads issued together with counted waits instead of 8 serialized load-wait-store groups
# speedup vs baseline: 1.0091x; 1.0091x over previous
.LBB0_3296:
	v_lshl_add_u32 v152, s4, 8, v1
	v_ashrrev_i32_e32 v153, 31, v152
	v_lshlrev_b64 v[148:149], 6, v[152:153]
	v_lshl_add_u64 v[148:149], v[138:139], 0, v[148:149]
	global_load_dwordx4 v[162:165], v[148:149], off
	v_add_co_u32_e32 v212, vcc, 0x2000, v148
	s_nop 1
	v_addc_co_u32_e32 v213, vcc, 0, v149, vcc
	global_load_dwordx4 v[184:187], v[148:149], off offset:1024
	global_load_dwordx4 v[188:191], v[148:149], off offset:2048
	global_load_dwordx4 v[192:195], v[148:149], off offset:3072
	global_load_dwordx4 v[196:199], v[212:213], off
	global_load_dwordx4 v[200:203], v[212:213], off offset:1024
	global_load_dwordx4 v[204:207], v[212:213], off offset:2048
	global_load_dwordx4 v[208:211], v[212:213], off offset:3072
	v_and_b32_e32 v153, 64, v159
	v_xor_b32_e32 v151, 16, v159
	v_add_u32_e32 v168, 64, v153
	v_cmp_lt_i32_e32 vcc, v151, v168
	v_xor_b32_e32 v161, 32, v159
	v_lshl_or_b32 v150, s5, 7, v155
	v_cndmask_b32_e32 v151, v159, v151, vcc
	v_lshlrev_b32_e32 v153, 2, v151
	v_cmp_lt_i32_e32 vcc, v161, v168
	v_mov_b64_e32 v[148:149], s[64:65]
	v_ashrrev_i32_e32 v151, 31, v150
	v_cndmask_b32_e32 v161, v159, v161, vcc
	v_lshlrev_b32_e32 v161, 2, v161
	v_lshlrev_b64 v[150:151], 1, v[150:151]
	s_waitcnt vmcnt(7)
	v_mov_b32_e32 v166, v163
	v_mov_b32_e32 v167, v164
	v_mov_b32_e32 v163, v165
	v_pk_add_f32 v[162:163], v[166:167], v[162:163]
	v_or_b32_e32 v164, 16, v152
	v_add_f32_e32 v162, v162, v163
	ds_bpermute_b32 v163, v153, v162
	v_ashrrev_i32_e32 v165, 31, v164
	s_waitcnt lgkmcnt(0)
	v_add_f32_e32 v166, v162, v163
	ds_bpermute_b32 v167, v161, v166
	v_mad_i64_i32 v[162:163], s[4:5], v152, s52, v[148:149]
	v_lshl_add_u64 v[162:163], v[162:163], 0, v[150:151]
	s_waitcnt lgkmcnt(0)
	v_add_f32_e32 v166, v166, v167
	v_fmamk_f32 v166, v166, 0x3a800000, v160
	v_mul_f32_e32 v167, 0x4b800000, v166
	v_cmp_gt_f32_e32 vcc, s51, v166
	s_nop 1
	v_cndmask_b32_e32 v166, v166, v167, vcc
	v_rsq_f32_e32 v168, v166
	v_lshlrev_b64 v[166:167], 6, v[164:165]
	v_lshl_add_u64 v[166:167], v[138:139], 0, v[166:167]
	v_mul_f32_e32 v165, 0x45800000, v168
	v_cndmask_b32_e32 v168, v168, v165, vcc
	v_pk_mul_f32 v[128:129], v[128:129], v[168:169] op_sel_hi:[1,0]
	v_pk_mul_f32 v[126:127], v[126:127], v[168:169] op_sel_hi:[1,0]
	v_pk_mul_f32 v[124:125], v[124:125], v[168:169] op_sel_hi:[1,0]
	v_pk_mul_f32 v[122:123], v[122:123], v[168:169] op_sel_hi:[1,0]
	v_pk_mul_f32 v[120:121], v[120:121], v[168:169] op_sel_hi:[1,0]
	v_pk_mul_f32 v[118:119], v[118:119], v[168:169] op_sel_hi:[1,0]
	v_pk_mul_f32 v[116:117], v[116:117], v[168:169] op_sel_hi:[1,0]
	v_pk_mul_f32 v[114:115], v[114:115], v[168:169] op_sel_hi:[1,0]
	v_mul_f32_e32 v165, 0xbfb8aa3b, v126
	v_mul_f32_e32 v168, 0xbfb8aa3b, v127
	v_mul_f32_e32 v169, 0xbfb8aa3b, v128
	v_mul_f32_e32 v170, 0xbfb8aa3b, v129
	v_mul_f32_e32 v171, 0xbfb8aa3b, v122
	v_mul_f32_e32 v172, 0xbfb8aa3b, v123
	v_mul_f32_e32 v173, 0xbfb8aa3b, v124
	v_mul_f32_e32 v174, 0xbfb8aa3b, v125
	v_exp_f32_e32 v165, v165
	v_exp_f32_e32 v168, v168
	v_exp_f32_e32 v169, v169
	v_exp_f32_e32 v170, v170
	v_exp_f32_e32 v171, v171
	v_exp_f32_e32 v172, v172
	v_exp_f32_e32 v173, v173
	v_exp_f32_e32 v174, v174
	v_add_f32_e32 v165, 1.0, v165
	v_add_f32_e32 v175, 1.0, v168
	v_add_f32_e32 v176, 1.0, v169
	v_add_f32_e32 v177, 1.0, v170
	v_add_f32_e32 v178, 1.0, v171
	v_add_f32_e32 v179, 1.0, v172
	v_add_f32_e32 v180, 1.0, v173
	v_add_f32_e32 v181, 1.0, v174
	v_rcp_f32_e32 v168, v165
	v_rcp_f32_e32 v169, v175
	v_rcp_f32_e32 v170, v176
	v_rcp_f32_e32 v171, v177
	v_rcp_f32_e32 v172, v178
	v_rcp_f32_e32 v173, v179
	v_rcp_f32_e32 v174, v180
	v_rcp_f32_e32 v175, v181
	v_pk_mul_f32 v[126:127], v[126:127], v[168:169]
	v_pk_mul_f32 v[128:129], v[128:129], v[170:171]
	v_pk_mul_f32 v[122:123], v[122:123], v[172:173]
	v_pk_mul_f32 v[124:125], v[124:125], v[174:175]
	v_pk_mul_f32 v[118:119], v[118:119], v[126:127]
	v_pk_mul_f32 v[120:121], v[120:121], v[128:129]
	v_pk_mul_f32 v[122:123], v[114:115], v[122:123]
	v_pk_mul_f32 v[124:125], v[116:117], v[124:125]
	v_cvt_pk_bf16_f32 v114, v118, v119
	v_cvt_pk_bf16_f32 v115, v120, v121
	v_cvt_pk_bf16_f32 v116, v122, v123
	v_cvt_pk_bf16_f32 v117, v124, v125
	global_store_dwordx4 v[162:163], v[114:117], off
	s_waitcnt vmcnt(7)
	s_nop 1
	v_mov_b32_e32 v114, v184
	v_mov_b32_e32 v115, v185
	v_mov_b32_e32 v116, v186
	v_mov_b32_e32 v117, v187
	v_mov_b32_e32 v118, v115
	v_mov_b32_e32 v119, v116
	v_mov_b32_e32 v115, v117
	v_pk_add_f32 v[114:115], v[118:119], v[114:115]
	v_mad_i64_i32 v[116:117], s[4:5], v164, s52, v[148:149]
	v_add_f32_e32 v114, v114, v115
	ds_bpermute_b32 v115, v153, v114
	v_lshl_add_u64 v[116:117], v[116:117], 0, v[150:151]
	s_waitcnt lgkmcnt(0)
	v_add_f32_e32 v118, v114, v115
	ds_bpermute_b32 v119, v161, v118
	v_or_b32_e32 v114, 32, v152
	v_ashrrev_i32_e32 v115, 31, v114
	s_waitcnt lgkmcnt(0)
	v_add_f32_e32 v118, v118, v119
	v_fmamk_f32 v118, v118, 0x3a800000, v160
	v_mul_f32_e32 v119, 0x4b800000, v118
	v_cmp_gt_f32_e32 vcc, s51, v118
	s_nop 1
	v_cndmask_b32_e32 v118, v118, v119, vcc
	v_rsq_f32_e32 v120, v118
	v_lshlrev_b64 v[118:119], 6, v[114:115]
	v_lshl_add_u64 v[118:119], v[138:139], 0, v[118:119]
	v_mul_f32_e32 v115, 0x45800000, v120
	v_cndmask_b32_e32 v120, v120, v115, vcc
	v_pk_mul_f32 v[112:113], v[112:113], v[120:121] op_sel_hi:[1,0]
	v_pk_mul_f32 v[110:111], v[110:111], v[120:121] op_sel_hi:[1,0]
	v_pk_mul_f32 v[108:109], v[108:109], v[120:121] op_sel_hi:[1,0]
	v_pk_mul_f32 v[106:107], v[106:107], v[120:121] op_sel_hi:[1,0]
	v_pk_mul_f32 v[104:105], v[104:105], v[120:121] op_sel_hi:[1,0]
	v_pk_mul_f32 v[102:103], v[102:103], v[120:121] op_sel_hi:[1,0]
	v_pk_mul_f32 v[100:101], v[100:101], v[120:121] op_sel_hi:[1,0]
	v_pk_mul_f32 v[98:99], v[98:99], v[120:121] op_sel_hi:[1,0]
	v_mul_f32_e32 v115, 0xbfb8aa3b, v110
	v_mul_f32_e32 v120, 0xbfb8aa3b, v111
	v_mul_f32_e32 v121, 0xbfb8aa3b, v112
	v_mul_f32_e32 v122, 0xbfb8aa3b, v113
	v_mul_f32_e32 v123, 0xbfb8aa3b, v106
	v_mul_f32_e32 v124, 0xbfb8aa3b, v107
	v_mul_f32_e32 v125, 0xbfb8aa3b, v108
	v_mul_f32_e32 v126, 0xbfb8aa3b, v109
	v_exp_f32_e32 v115, v115
	v_exp_f32_e32 v120, v120
	v_exp_f32_e32 v121, v121
	v_exp_f32_e32 v122, v122
	v_exp_f32_e32 v123, v123
	v_exp_f32_e32 v124, v124
	v_exp_f32_e32 v125, v125
	v_exp_f32_e32 v126, v126
	v_add_f32_e32 v115, 1.0, v115
	v_add_f32_e32 v127, 1.0, v120
	v_add_f32_e32 v128, 1.0, v121
	v_add_f32_e32 v129, 1.0, v122
	v_add_f32_e32 v162, 1.0, v123
	v_add_f32_e32 v163, 1.0, v124
	v_add_f32_e32 v164, 1.0, v125
	v_add_f32_e32 v165, 1.0, v126
	v_rcp_f32_e32 v120, v115
	v_rcp_f32_e32 v121, v127
	v_rcp_f32_e32 v122, v128
	v_rcp_f32_e32 v123, v129
	v_rcp_f32_e32 v124, v162
	v_rcp_f32_e32 v125, v163
	v_rcp_f32_e32 v126, v164
	v_rcp_f32_e32 v127, v165
	v_pk_mul_f32 v[110:111], v[110:111], v[120:121]
	v_pk_mul_f32 v[112:113], v[112:113], v[122:123]
	v_pk_mul_f32 v[106:107], v[106:107], v[124:125]
	v_pk_mul_f32 v[108:109], v[108:109], v[126:127]
	v_pk_mul_f32 v[102:103], v[102:103], v[110:111]
	v_pk_mul_f32 v[104:105], v[104:105], v[112:113]
	v_pk_mul_f32 v[106:107], v[98:99], v[106:107]
	v_pk_mul_f32 v[108:109], v[100:101], v[108:109]
	v_cvt_pk_bf16_f32 v98, v102, v103
	v_cvt_pk_bf16_f32 v99, v104, v105
	v_cvt_pk_bf16_f32 v100, v106, v107
	v_cvt_pk_bf16_f32 v101, v108, v109
	global_store_dwordx4 v[116:117], v[98:101], off
	s_waitcnt vmcnt(7)
	s_nop 1
	v_mov_b32_e32 v98, v188
	v_mov_b32_e32 v99, v189
	v_mov_b32_e32 v100, v190
	v_mov_b32_e32 v101, v191
	v_mov_b32_e32 v102, v99
	v_mov_b32_e32 v103, v100
	v_mov_b32_e32 v99, v101
	v_pk_add_f32 v[98:99], v[102:103], v[98:99]
	v_mad_i64_i32 v[100:101], s[4:5], v114, s52, v[148:149]
	v_add_f32_e32 v98, v98, v99
	ds_bpermute_b32 v99, v153, v98
	v_lshl_add_u64 v[100:101], v[100:101], 0, v[150:151]
	s_waitcnt lgkmcnt(0)
	v_add_f32_e32 v102, v98, v99
	ds_bpermute_b32 v103, v161, v102
	v_or_b32_e32 v98, 48, v152
	v_ashrrev_i32_e32 v99, 31, v98
	s_waitcnt lgkmcnt(0)
	v_add_f32_e32 v102, v102, v103
	v_fmamk_f32 v102, v102, 0x3a800000, v160
	v_mul_f32_e32 v103, 0x4b800000, v102
	v_cmp_gt_f32_e32 vcc, s51, v102
	s_nop 1
	v_cndmask_b32_e32 v102, v102, v103, vcc
	v_rsq_f32_e32 v104, v102
	v_lshlrev_b64 v[102:103], 6, v[98:99]
	v_lshl_add_u64 v[102:103], v[138:139], 0, v[102:103]
	v_mul_f32_e32 v99, 0x45800000, v104
	v_cndmask_b32_e32 v104, v104, v99, vcc
	v_pk_mul_f32 v[96:97], v[96:97], v[104:105] op_sel_hi:[1,0]
	v_pk_mul_f32 v[94:95], v[94:95], v[104:105] op_sel_hi:[1,0]
	v_pk_mul_f32 v[92:93], v[92:93], v[104:105] op_sel_hi:[1,0]
	v_pk_mul_f32 v[90:91], v[90:91], v[104:105] op_sel_hi:[1,0]
	v_pk_mul_f32 v[88:89], v[88:89], v[104:105] op_sel_hi:[1,0]
	v_pk_mul_f32 v[86:87], v[86:87], v[104:105] op_sel_hi:[1,0]
	v_pk_mul_f32 v[84:85], v[84:85], v[104:105] op_sel_hi:[1,0]
	v_pk_mul_f32 v[82:83], v[82:83], v[104:105] op_sel_hi:[1,0]
	v_mul_f32_e32 v99, 0xbfb8aa3b, v94
	v_mul_f32_e32 v104, 0xbfb8aa3b, v95
	v_mul_f32_e32 v105, 0xbfb8aa3b, v96
	v_mul_f32_e32 v106, 0xbfb8aa3b, v97
	v_mul_f32_e32 v107, 0xbfb8aa3b, v90
	v_mul_f32_e32 v108, 0xbfb8aa3b, v91
	v_mul_f32_e32 v109, 0xbfb8aa3b, v92
	v_mul_f32_e32 v110, 0xbfb8aa3b, v93
	v_exp_f32_e32 v99, v99
	v_exp_f32_e32 v104, v104
	v_exp_f32_e32 v105, v105
	v_exp_f32_e32 v106, v106
	v_exp_f32_e32 v107, v107
	v_exp_f32_e32 v108, v108
	v_exp_f32_e32 v109, v109
	v_exp_f32_e32 v110, v110
	v_add_f32_e32 v99, 1.0, v99
	v_add_f32_e32 v111, 1.0, v104
	v_add_f32_e32 v112, 1.0, v105
	v_add_f32_e32 v113, 1.0, v106
	v_add_f32_e32 v114, 1.0, v107
	v_add_f32_e32 v115, 1.0, v108
	v_add_f32_e32 v116, 1.0, v109
	v_add_f32_e32 v117, 1.0, v110
	v_rcp_f32_e32 v104, v99
	v_rcp_f32_e32 v105, v111
	v_rcp_f32_e32 v106, v112
	v_rcp_f32_e32 v107, v113
	v_rcp_f32_e32 v108, v114
	v_rcp_f32_e32 v109, v115
	v_rcp_f32_e32 v110, v116
	v_rcp_f32_e32 v111, v117
	v_pk_mul_f32 v[94:95], v[94:95], v[104:105]
	v_pk_mul_f32 v[96:97], v[96:97], v[106:107]
	v_pk_mul_f32 v[90:91], v[90:91], v[108:109]
	v_pk_mul_f32 v[92:93], v[92:93], v[110:111]
	v_pk_mul_f32 v[86:87], v[86:87], v[94:95]
	v_pk_mul_f32 v[88:89], v[88:89], v[96:97]
	v_pk_mul_f32 v[90:91], v[82:83], v[90:91]
	v_pk_mul_f32 v[92:93], v[84:85], v[92:93]
	v_cvt_pk_bf16_f32 v82, v86, v87
	v_cvt_pk_bf16_f32 v83, v88, v89
	v_cvt_pk_bf16_f32 v84, v90, v91
	v_cvt_pk_bf16_f32 v85, v92, v93
	global_store_dwordx4 v[100:101], v[82:85], off
	s_waitcnt vmcnt(7)
	s_nop 1
	v_mov_b32_e32 v82, v192
	v_mov_b32_e32 v83, v193
	v_mov_b32_e32 v84, v194
	v_mov_b32_e32 v85, v195
	v_mov_b32_e32 v86, v83
	v_mov_b32_e32 v87, v84
	v_mov_b32_e32 v83, v85
	v_pk_add_f32 v[82:83], v[86:87], v[82:83]
	v_mad_i64_i32 v[84:85], s[4:5], v98, s52, v[148:149]
	v_add_f32_e32 v82, v82, v83
	ds_bpermute_b32 v83, v153, v82
	v_lshl_add_u64 v[84:85], v[84:85], 0, v[150:151]
	s_waitcnt lgkmcnt(0)
	v_add_f32_e32 v86, v82, v83
	ds_bpermute_b32 v87, v161, v86
	v_add_u32_e32 v82, 0x80, v152
	v_ashrrev_i32_e32 v83, 31, v82
	s_waitcnt lgkmcnt(0)
	v_add_f32_e32 v86, v86, v87
	v_fmamk_f32 v86, v86, 0x3a800000, v160
	v_mul_f32_e32 v87, 0x4b800000, v86
	v_cmp_gt_f32_e32 vcc, s51, v86
	s_nop 1
	v_cndmask_b32_e32 v86, v86, v87, vcc
	v_rsq_f32_e32 v88, v86
	v_lshlrev_b64 v[86:87], 6, v[82:83]
	v_lshl_add_u64 v[86:87], v[138:139], 0, v[86:87]
	v_mul_f32_e32 v83, 0x45800000, v88
	v_cndmask_b32_e32 v88, v88, v83, vcc
	v_pk_mul_f32 v[80:81], v[80:81], v[88:89] op_sel_hi:[1,0]
	v_pk_mul_f32 v[78:79], v[78:79], v[88:89] op_sel_hi:[1,0]
	v_pk_mul_f32 v[76:77], v[76:77], v[88:89] op_sel_hi:[1,0]
	v_pk_mul_f32 v[74:75], v[74:75], v[88:89] op_sel_hi:[1,0]
	v_pk_mul_f32 v[72:73], v[72:73], v[88:89] op_sel_hi:[1,0]
	v_pk_mul_f32 v[70:71], v[70:71], v[88:89] op_sel_hi:[1,0]
	v_pk_mul_f32 v[68:69], v[68:69], v[88:89] op_sel_hi:[1,0]
	v_pk_mul_f32 v[66:67], v[66:67], v[88:89] op_sel_hi:[1,0]
	v_mul_f32_e32 v83, 0xbfb8aa3b, v78
	v_mul_f32_e32 v88, 0xbfb8aa3b, v79
	v_mul_f32_e32 v89, 0xbfb8aa3b, v80
	v_mul_f32_e32 v90, 0xbfb8aa3b, v81
	v_mul_f32_e32 v91, 0xbfb8aa3b, v74
	v_mul_f32_e32 v92, 0xbfb8aa3b, v75
	v_mul_f32_e32 v93, 0xbfb8aa3b, v76
	v_mul_f32_e32 v94, 0xbfb8aa3b, v77
	v_exp_f32_e32 v83, v83
	v_exp_f32_e32 v88, v88
	v_exp_f32_e32 v89, v89
	v_exp_f32_e32 v90, v90
	v_exp_f32_e32 v91, v91
	v_exp_f32_e32 v92, v92
	v_exp_f32_e32 v93, v93
	v_exp_f32_e32 v94, v94
	v_add_f32_e32 v83, 1.0, v83
	v_add_f32_e32 v95, 1.0, v88
	v_add_f32_e32 v96, 1.0, v89
	v_add_f32_e32 v97, 1.0, v90
	v_add_f32_e32 v98, 1.0, v91
	v_add_f32_e32 v99, 1.0, v92
	v_add_f32_e32 v100, 1.0, v93
	v_add_f32_e32 v101, 1.0, v94
	v_rcp_f32_e32 v88, v83
	v_rcp_f32_e32 v89, v95
	v_rcp_f32_e32 v90, v96
	v_rcp_f32_e32 v91, v97
	v_rcp_f32_e32 v92, v98
	v_rcp_f32_e32 v93, v99
	v_rcp_f32_e32 v94, v100
	v_rcp_f32_e32 v95, v101
	v_pk_mul_f32 v[78:79], v[78:79], v[88:89]
	v_pk_mul_f32 v[80:81], v[80:81], v[90:91]
	v_pk_mul_f32 v[74:75], v[74:75], v[92:93]
	v_pk_mul_f32 v[76:77], v[76:77], v[94:95]
	v_pk_mul_f32 v[70:71], v[70:71], v[78:79]
	v_pk_mul_f32 v[72:73], v[72:73], v[80:81]
	v_pk_mul_f32 v[74:75], v[66:67], v[74:75]
	v_pk_mul_f32 v[76:77], v[68:69], v[76:77]
	v_cvt_pk_bf16_f32 v66, v70, v71
	v_cvt_pk_bf16_f32 v67, v72, v73
	v_cvt_pk_bf16_f32 v68, v74, v75
	v_cvt_pk_bf16_f32 v69, v76, v77
	global_store_dwordx4 v[84:85], v[66:69], off
	s_waitcnt vmcnt(7)
	s_nop 1
	v_mov_b32_e32 v66, v196
	v_mov_b32_e32 v67, v197
	v_mov_b32_e32 v68, v198
	v_mov_b32_e32 v69, v199
	v_mov_b32_e32 v70, v67
	v_mov_b32_e32 v71, v68
	v_mov_b32_e32 v67, v69
	v_pk_add_f32 v[66:67], v[70:71], v[66:67]
	v_mad_i64_i32 v[68:69], s[4:5], v82, s52, v[148:149]
	v_add_f32_e32 v66, v66, v67
	ds_bpermute_b32 v67, v153, v66
	v_lshl_add_u64 v[68:69], v[68:69], 0, v[150:151]
	s_waitcnt lgkmcnt(0)
	v_add_f32_e32 v70, v66, v67
	ds_bpermute_b32 v71, v161, v70
	v_add_u32_e32 v66, 0x90, v152
	v_ashrrev_i32_e32 v67, 31, v66
	s_waitcnt lgkmcnt(0)
	v_add_f32_e32 v70, v70, v71
	v_fmamk_f32 v70, v70, 0x3a800000, v160
	v_mul_f32_e32 v71, 0x4b800000, v70
	v_cmp_gt_f32_e32 vcc, s51, v70
	s_nop 1
	v_cndmask_b32_e32 v70, v70, v71, vcc
	v_rsq_f32_e32 v72, v70
	v_lshlrev_b64 v[70:71], 6, v[66:67]
	v_lshl_add_u64 v[70:71], v[138:139], 0, v[70:71]
	v_mul_f32_e32 v67, 0x45800000, v72
	v_cndmask_b32_e32 v72, v72, v67, vcc
	v_pk_mul_f32 v[64:65], v[64:65], v[72:73] op_sel_hi:[1,0]
	v_pk_mul_f32 v[62:63], v[62:63], v[72:73] op_sel_hi:[1,0]
	v_pk_mul_f32 v[60:61], v[60:61], v[72:73] op_sel_hi:[1,0]
	v_pk_mul_f32 v[58:59], v[58:59], v[72:73] op_sel_hi:[1,0]
	v_pk_mul_f32 v[56:57], v[56:57], v[72:73] op_sel_hi:[1,0]
	v_pk_mul_f32 v[54:55], v[54:55], v[72:73] op_sel_hi:[1,0]
	v_pk_mul_f32 v[52:53], v[52:53], v[72:73] op_sel_hi:[1,0]
	v_pk_mul_f32 v[50:51], v[50:51], v[72:73] op_sel_hi:[1,0]
	v_mul_f32_e32 v67, 0xbfb8aa3b, v62
	v_mul_f32_e32 v72, 0xbfb8aa3b, v63
	v_mul_f32_e32 v73, 0xbfb8aa3b, v64
	v_mul_f32_e32 v74, 0xbfb8aa3b, v65
	v_mul_f32_e32 v75, 0xbfb8aa3b, v58
	v_mul_f32_e32 v76, 0xbfb8aa3b, v59
	v_mul_f32_e32 v77, 0xbfb8aa3b, v60
	v_mul_f32_e32 v78, 0xbfb8aa3b, v61
	v_exp_f32_e32 v67, v67
	v_exp_f32_e32 v72, v72
	v_exp_f32_e32 v73, v73
	v_exp_f32_e32 v74, v74
	v_exp_f32_e32 v75, v75
	v_exp_f32_e32 v76, v76
	v_exp_f32_e32 v77, v77
	v_exp_f32_e32 v78, v78
	v_add_f32_e32 v67, 1.0, v67
	v_add_f32_e32 v79, 1.0, v72
	v_add_f32_e32 v80, 1.0, v73
	v_add_f32_e32 v81, 1.0, v74
	v_add_f32_e32 v82, 1.0, v75
	v_add_f32_e32 v83, 1.0, v76
	v_add_f32_e32 v84, 1.0, v77
	v_add_f32_e32 v85, 1.0, v78
	v_rcp_f32_e32 v72, v67
	v_rcp_f32_e32 v73, v79
	v_rcp_f32_e32 v74, v80
	v_rcp_f32_e32 v75, v81
	v_rcp_f32_e32 v76, v82
	v_rcp_f32_e32 v77, v83
	v_rcp_f32_e32 v78, v84
	v_rcp_f32_e32 v79, v85
	v_pk_mul_f32 v[62:63], v[62:63], v[72:73]
	v_pk_mul_f32 v[64:65], v[64:65], v[74:75]
	v_pk_mul_f32 v[58:59], v[58:59], v[76:77]
	v_pk_mul_f32 v[60:61], v[60:61], v[78:79]
	v_pk_mul_f32 v[54:55], v[54:55], v[62:63]
	v_pk_mul_f32 v[56:57], v[56:57], v[64:65]
	v_pk_mul_f32 v[58:59], v[50:51], v[58:59]
	v_pk_mul_f32 v[60:61], v[52:53], v[60:61]
	v_cvt_pk_bf16_f32 v50, v54, v55
	v_cvt_pk_bf16_f32 v51, v56, v57
	v_cvt_pk_bf16_f32 v52, v58, v59
	v_cvt_pk_bf16_f32 v53, v60, v61
	global_store_dwordx4 v[68:69], v[50:53], off
	s_waitcnt vmcnt(7)
	s_nop 1
	v_mov_b32_e32 v50, v200
	v_mov_b32_e32 v51, v201
	v_mov_b32_e32 v52, v202
	v_mov_b32_e32 v53, v203
	v_mov_b32_e32 v54, v51
	v_mov_b32_e32 v55, v52
	v_mov_b32_e32 v51, v53
	v_pk_add_f32 v[50:51], v[54:55], v[50:51]
	v_mad_i64_i32 v[52:53], s[4:5], v66, s52, v[148:149]
	v_add_f32_e32 v50, v50, v51
	ds_bpermute_b32 v51, v153, v50
	v_lshl_add_u64 v[52:53], v[52:53], 0, v[150:151]
	s_waitcnt lgkmcnt(0)
	v_add_f32_e32 v54, v50, v51
	ds_bpermute_b32 v55, v161, v54
	v_add_u32_e32 v50, 0xa0, v152
	v_ashrrev_i32_e32 v51, 31, v50
	s_waitcnt lgkmcnt(0)
	v_add_f32_e32 v54, v54, v55
	v_fmamk_f32 v54, v54, 0x3a800000, v160
	v_mul_f32_e32 v55, 0x4b800000, v54
	v_cmp_gt_f32_e32 vcc, s51, v54
	s_nop 1
	v_cndmask_b32_e32 v54, v54, v55, vcc
	v_rsq_f32_e32 v56, v54
	v_lshlrev_b64 v[54:55], 6, v[50:51]
	v_lshl_add_u64 v[54:55], v[138:139], 0, v[54:55]
	v_mul_f32_e32 v51, 0x45800000, v56
	v_cndmask_b32_e32 v56, v56, v51, vcc
	v_pk_mul_f32 v[48:49], v[48:49], v[56:57] op_sel_hi:[1,0]
	v_pk_mul_f32 v[46:47], v[46:47], v[56:57] op_sel_hi:[1,0]
	v_pk_mul_f32 v[44:45], v[44:45], v[56:57] op_sel_hi:[1,0]
	v_pk_mul_f32 v[42:43], v[42:43], v[56:57] op_sel_hi:[1,0]
	v_pk_mul_f32 v[40:41], v[40:41], v[56:57] op_sel_hi:[1,0]
	v_pk_mul_f32 v[38:39], v[38:39], v[56:57] op_sel_hi:[1,0]
	v_pk_mul_f32 v[36:37], v[36:37], v[56:57] op_sel_hi:[1,0]
	v_pk_mul_f32 v[34:35], v[34:35], v[56:57] op_sel_hi:[1,0]
	v_mul_f32_e32 v51, 0xbfb8aa3b, v46
	v_mul_f32_e32 v56, 0xbfb8aa3b, v47
	v_mul_f32_e32 v57, 0xbfb8aa3b, v48
	v_mul_f32_e32 v58, 0xbfb8aa3b, v49
	v_mul_f32_e32 v59, 0xbfb8aa3b, v42
	v_mul_f32_e32 v60, 0xbfb8aa3b, v43
	v_mul_f32_e32 v61, 0xbfb8aa3b, v44
	v_mul_f32_e32 v62, 0xbfb8aa3b, v45
	v_exp_f32_e32 v51, v51
	v_exp_f32_e32 v56, v56
	v_exp_f32_e32 v57, v57
	v_exp_f32_e32 v58, v58
	v_exp_f32_e32 v59, v59
	v_exp_f32_e32 v60, v60
	v_exp_f32_e32 v61, v61
	v_exp_f32_e32 v62, v62
	v_add_f32_e32 v51, 1.0, v51
	v_add_f32_e32 v63, 1.0, v56
	v_add_f32_e32 v64, 1.0, v57
	v_add_f32_e32 v65, 1.0, v58
	v_add_f32_e32 v66, 1.0, v59
	v_add_f32_e32 v67, 1.0, v60
	v_add_f32_e32 v68, 1.0, v61
	v_add_f32_e32 v69, 1.0, v62
	v_rcp_f32_e32 v56, v51
	v_rcp_f32_e32 v57, v63
	v_rcp_f32_e32 v58, v64
	v_rcp_f32_e32 v59, v65
	v_rcp_f32_e32 v60, v66
	v_rcp_f32_e32 v61, v67
	v_rcp_f32_e32 v62, v68
	v_rcp_f32_e32 v63, v69
	v_pk_mul_f32 v[46:47], v[46:47], v[56:57]
	v_pk_mul_f32 v[48:49], v[48:49], v[58:59]
	v_pk_mul_f32 v[42:43], v[42:43], v[60:61]
	v_pk_mul_f32 v[44:45], v[44:45], v[62:63]
	v_pk_mul_f32 v[38:39], v[38:39], v[46:47]
	v_pk_mul_f32 v[40:41], v[40:41], v[48:49]
	v_pk_mul_f32 v[42:43], v[34:35], v[42:43]
	v_pk_mul_f32 v[44:45], v[36:37], v[44:45]
	v_cvt_pk_bf16_f32 v34, v38, v39
	v_cvt_pk_bf16_f32 v35, v40, v41
	v_cvt_pk_bf16_f32 v36, v42, v43
	v_cvt_pk_bf16_f32 v37, v44, v45
	global_store_dwordx4 v[52:53], v[34:37], off
	s_waitcnt vmcnt(7)
	s_nop 1
	v_mov_b32_e32 v34, v204
	v_mov_b32_e32 v35, v205
	v_mov_b32_e32 v36, v206
	v_mov_b32_e32 v37, v207
	v_mov_b32_e32 v38, v35
	v_mov_b32_e32 v39, v36
	v_mov_b32_e32 v35, v37
	v_pk_add_f32 v[34:35], v[38:39], v[34:35]
	v_mad_i64_i32 v[36:37], s[4:5], v50, s52, v[148:149]
	v_add_f32_e32 v34, v34, v35
	ds_bpermute_b32 v35, v153, v34
	v_lshl_add_u64 v[36:37], v[36:37], 0, v[150:151]
	s_waitcnt lgkmcnt(0)
	v_add_f32_e32 v38, v34, v35
	ds_bpermute_b32 v39, v161, v38
	v_add_u32_e32 v34, 0xb0, v152
	v_ashrrev_i32_e32 v35, 31, v34
	s_waitcnt lgkmcnt(0)
	v_add_f32_e32 v38, v38, v39
	v_fmamk_f32 v38, v38, 0x3a800000, v160
	v_mul_f32_e32 v39, 0x4b800000, v38
	v_cmp_gt_f32_e32 vcc, s51, v38
	s_nop 1
	v_cndmask_b32_e32 v38, v38, v39, vcc
	v_rsq_f32_e32 v40, v38
	v_lshlrev_b64 v[38:39], 6, v[34:35]
	v_lshl_add_u64 v[38:39], v[138:139], 0, v[38:39]
	v_mul_f32_e32 v35, 0x45800000, v40
	v_cndmask_b32_e32 v40, v40, v35, vcc
	v_pk_mul_f32 v[32:33], v[32:33], v[40:41] op_sel_hi:[1,0]
	v_pk_mul_f32 v[30:31], v[30:31], v[40:41] op_sel_hi:[1,0]
	v_pk_mul_f32 v[28:29], v[28:29], v[40:41] op_sel_hi:[1,0]
	v_pk_mul_f32 v[26:27], v[26:27], v[40:41] op_sel_hi:[1,0]
	v_pk_mul_f32 v[24:25], v[24:25], v[40:41] op_sel_hi:[1,0]
	v_pk_mul_f32 v[22:23], v[22:23], v[40:41] op_sel_hi:[1,0]
	v_pk_mul_f32 v[20:21], v[20:21], v[40:41] op_sel_hi:[1,0]
	v_pk_mul_f32 v[18:19], v[18:19], v[40:41] op_sel_hi:[1,0]
	v_mul_f32_e32 v35, 0xbfb8aa3b, v30
	v_mul_f32_e32 v40, 0xbfb8aa3b, v31
	v_mul_f32_e32 v41, 0xbfb8aa3b, v32
	v_mul_f32_e32 v42, 0xbfb8aa3b, v33
	v_mul_f32_e32 v43, 0xbfb8aa3b, v26
	v_mul_f32_e32 v44, 0xbfb8aa3b, v27
	v_mul_f32_e32 v45, 0xbfb8aa3b, v28
	v_mul_f32_e32 v46, 0xbfb8aa3b, v29
	v_exp_f32_e32 v35, v35
	v_exp_f32_e32 v40, v40
	v_exp_f32_e32 v41, v41
	v_exp_f32_e32 v42, v42
	v_exp_f32_e32 v43, v43
	v_exp_f32_e32 v44, v44
	v_exp_f32_e32 v45, v45
	v_exp_f32_e32 v46, v46
	v_add_f32_e32 v35, 1.0, v35
	v_add_f32_e32 v47, 1.0, v40
	v_add_f32_e32 v48, 1.0, v41
	v_add_f32_e32 v49, 1.0, v42
	v_add_f32_e32 v50, 1.0, v43
	v_add_f32_e32 v51, 1.0, v44
	v_add_f32_e32 v52, 1.0, v45
	v_add_f32_e32 v53, 1.0, v46
	v_rcp_f32_e32 v40, v35
	v_rcp_f32_e32 v41, v47
	v_rcp_f32_e32 v42, v48
	v_rcp_f32_e32 v43, v49
	v_rcp_f32_e32 v44, v50
	v_rcp_f32_e32 v45, v51
	v_rcp_f32_e32 v46, v52
	v_rcp_f32_e32 v47, v53
	v_pk_mul_f32 v[30:31], v[30:31], v[40:41]
	v_pk_mul_f32 v[32:33], v[32:33], v[42:43]
	v_pk_mul_f32 v[26:27], v[26:27], v[44:45]
	v_pk_mul_f32 v[28:29], v[28:29], v[46:47]
	v_pk_mul_f32 v[22:23], v[22:23], v[30:31]
	v_pk_mul_f32 v[24:25], v[24:25], v[32:33]
	v_pk_mul_f32 v[26:27], v[18:19], v[26:27]
	v_pk_mul_f32 v[28:29], v[20:21], v[28:29]
	v_cvt_pk_bf16_f32 v18, v22, v23
	v_cvt_pk_bf16_f32 v19, v24, v25
	v_cvt_pk_bf16_f32 v20, v26, v27
	v_cvt_pk_bf16_f32 v21, v28, v29
	global_store_dwordx4 v[36:37], v[18:21], off
	s_waitcnt vmcnt(7)
	s_nop 1
	v_mov_b32_e32 v18, v208
	v_mov_b32_e32 v19, v209
	v_mov_b32_e32 v20, v210
	v_mov_b32_e32 v21, v211
	s_andn2_b64 vcc, exec, s[0:1]
	s_mov_b64 s[0:1], -1
	v_mov_b32_e32 v22, v19
	v_mov_b32_e32 v23, v20
	v_mov_b32_e32 v19, v21
	v_pk_add_f32 v[18:19], v[22:23], v[18:19]
	s_nop 0
	v_add_f32_e32 v18, v18, v19
	ds_bpermute_b32 v19, v153, v18
	s_waitcnt lgkmcnt(0)
	v_add_f32_e32 v18, v18, v19
	ds_bpermute_b32 v19, v161, v18
	s_waitcnt lgkmcnt(0)
	v_add_f32_e32 v18, v18, v19
	v_fmamk_f32 v18, v18, 0x3a800000, v160
	v_mul_f32_e32 v19, 0x4b800000, v18
	v_cmp_gt_f32_e64 s[4:5], s51, v18
	s_nop 1
	v_cndmask_b32_e64 v18, v18, v19, s[4:5]
	v_rsq_f32_e32 v20, v18
	v_mad_i64_i32 v[18:19], s[22:23], v34, s52, v[148:149]
	v_lshl_add_u64 v[18:19], v[18:19], 0, v[150:151]
	v_mul_f32_e32 v21, 0x45800000, v20
	v_cndmask_b32_e64 v20, v20, v21, s[4:5]
	v_pk_mul_f32 v[16:17], v[16:17], v[20:21] op_sel_hi:[1,0]
	v_pk_mul_f32 v[14:15], v[14:15], v[20:21] op_sel_hi:[1,0]
	v_pk_mul_f32 v[12:13], v[12:13], v[20:21] op_sel_hi:[1,0]
	v_pk_mul_f32 v[10:11], v[10:11], v[20:21] op_sel_hi:[1,0]
	v_pk_mul_f32 v[8:9], v[8:9], v[20:21] op_sel_hi:[1,0]
	v_pk_mul_f32 v[6:7], v[6:7], v[20:21] op_sel_hi:[1,0]
	v_pk_mul_f32 v[4:5], v[4:5], v[20:21] op_sel_hi:[1,0]
	v_pk_mul_f32 v[2:3], v[2:3], v[20:21] op_sel_hi:[1,0]
	v_mul_f32_e32 v20, 0xbfb8aa3b, v14
	v_mul_f32_e32 v21, 0xbfb8aa3b, v15
	v_mul_f32_e32 v22, 0xbfb8aa3b, v16
	v_mul_f32_e32 v23, 0xbfb8aa3b, v17
	v_mul_f32_e32 v24, 0xbfb8aa3b, v10
	v_mul_f32_e32 v25, 0xbfb8aa3b, v11
	v_mul_f32_e32 v26, 0xbfb8aa3b, v12
	v_mul_f32_e32 v27, 0xbfb8aa3b, v13
	v_exp_f32_e32 v20, v20
	v_exp_f32_e32 v21, v21
	v_exp_f32_e32 v22, v22
	v_exp_f32_e32 v23, v23
	v_exp_f32_e32 v24, v24
	v_exp_f32_e32 v25, v25
	v_exp_f32_e32 v26, v26
	v_exp_f32_e32 v27, v27
	v_add_f32_e32 v20, 1.0, v20
	v_add_f32_e32 v21, 1.0, v21
	v_add_f32_e32 v22, 1.0, v22
	v_add_f32_e32 v23, 1.0, v23
	v_add_f32_e32 v24, 1.0, v24
	v_add_f32_e32 v25, 1.0, v25
	v_add_f32_e32 v26, 1.0, v26
	v_add_f32_e32 v27, 1.0, v27
	v_rcp_f32_e32 v20, v20
	v_rcp_f32_e32 v21, v21
	v_rcp_f32_e32 v22, v22
	v_rcp_f32_e32 v23, v23
	v_rcp_f32_e32 v24, v24
	v_rcp_f32_e32 v25, v25
	v_rcp_f32_e32 v26, v26
	v_rcp_f32_e32 v27, v27
	v_pk_mul_f32 v[14:15], v[14:15], v[20:21]
	v_pk_mul_f32 v[16:17], v[16:17], v[22:23]
	v_pk_mul_f32 v[10:11], v[10:11], v[24:25]
	v_pk_mul_f32 v[12:13], v[12:13], v[26:27]
	v_pk_mul_f32 v[6:7], v[6:7], v[14:15]
	v_pk_mul_f32 v[8:9], v[8:9], v[16:17]
	v_pk_mul_f32 v[10:11], v[2:3], v[10:11]
	v_pk_mul_f32 v[12:13], v[4:5], v[12:13]
	v_cvt_pk_bf16_f32 v2, v6, v7
	v_cvt_pk_bf16_f32 v3, v8, v9
	v_cvt_pk_bf16_f32 v4, v10, v11
	v_cvt_pk_bf16_f32 v5, v12, v13
	global_store_dwordx4 v[18:19], v[2:5], off
	s_cbranch_vccnz .LBB0_3285
	s_andn2_b64 vcc, exec, s[8:9]
	s_cbranch_vccnz .LBB0_3284
	s_barrier
	s_branch .LBB0_3284
